# attention PV section: 7 V-fragment ds_read_b64_tr_b16 pairs issued one block earlier into free quads (bias/S-ring regs), MFMA srcA renamed, lgkmcnt recounted
# speedup vs baseline: 1.0050x; 1.0050x over previous
; #define LAS __attribute__((address_space(3)))
; __device__ __forceinline__ unsigned pk2(float lo, float hi) { return f2bf(lo) | (f2bf(hi) << 16); }
; #define MFMA16(a, b, c) __builtin_amdgcn_mfma_f32_16x16x32_bf16(a, b, c, 0, 0, 0)
; __device__ __forceinline__ v4i16_t vtr(const LAS unsigned char* p) { return __builtin_amdgcn_ds_read_tr16_b64_v4i16((LAS v4i16_t*)p); }
; __device__ __forceinline__ void attn_phase(const Params& p, LAS unsigned char* lds, const int bx, const int G, const int tid) {
;     ...
;         const int qi = 16 * wq + fr; float mx = -3e38f;
; #pragma unroll
;         for (int j = 0; j < 9; ++j)
; #pragma unroll
;             for (int e = 0; e < 4; ++e) { const int u = 16 * (wq + j) + 4 * fq + e, jk = X.nb * 64 - 64 + u, dl = u - 64 - qi; const bool ok = jk >= 0 && jk < X.n && dl >= -64 && dl <= 64;
;                 const float b = ((const LAS float*)(L + AT_BIAS))[ok ? dl + 64 : 0]; const float sv = ok ? st[j][e] + b : -1e30f; st[j][e] = sv; mx = fmaxf(mx, sv); }
;         mx = fmaxf(mx, __shfl_xor(mx, 16)); mx = fmaxf(mx, __shfl_xor(mx, 32));
;         float sm = 0.f;
; #pragma unroll
;         for (int j = 0; j < 9; ++j)
; #pragma unroll
;             for (int e = 0; e < 4; ++e) { const float pv = __expf(st[j][e] - mx); st[j][e] = pv; sm += pv; }
;         sm += __shfl_xor(sm, 16); sm += __shfl_xor(sm, 32);
;         f32x4 ot[4];
; #pragma unroll
;         for (int dt = 0; dt < 4; ++dt) ot[dt] = (f32x4){0.f, 0.f, 0.f, 0.f};
; #pragma unroll
;         for (int ks = 0; ks < 5; ++ks) { v4u pw; pw.x = pk2(st[2 * ks][0], st[2 * ks][1]); pw.y = pk2(st[2 * ks][2], st[2 * ks][3]); pw.z = pk2(st[2 * ks + 1][0], st[2 * ks + 1][1]); pw.w = pk2(st[2 * ks + 1][2], st[2 * ks + 1][3]);
;             const bf16x8 pb = __builtin_bit_cast(bf16x8, pw);
; #pragma unroll
;             for (int dt = 0; dt < 4; ++dt) { const LAS unsigned char* vr = vbp + ks * 5120 + dt * 32;
;                 const v4i16_t lo = vtr(vr), hi = vtr(vr + 16 * 160);
;                 ot[dt] = MFMA16(__builtin_shufflevector(lo, hi, 0, 1, 2, 3, 4, 5, 6, 7), pb, ot[dt]); } }
.LBB0_487:
	s_or_b64 exec, exec, s[12:13]
	s_mov_b32 s2, 0xff61b1e6
	v_max3_f32 v60, v66, s2, v65
	v_max3_f32 v60, v60, v96, v67
	v_max3_f32 v60, v60, v98, v97
	v_max3_f32 v60, v60, v93, v92
	v_max3_f32 v60, v60, v95, v94
	v_max3_f32 v60, v60, v89, v88
	v_max3_f32 v60, v60, v91, v90
	v_max3_f32 v60, v60, v85, v84
	v_max3_f32 v60, v60, v87, v86
	v_max3_f32 v60, v60, v99, v80
	v_max3_f32 v60, v60, v82, v81
	v_max3_f32 v60, v60, v83, v76
	v_max3_f32 v60, v60, v188, v187
	v_max3_f32 v60, v60, v73, v72
	v_max3_f32 v60, v60, v75, v74
	v_max3_f32 v60, v60, v190, v68
	v_max3_f32 v60, v60, v192, v191
	v_max3_f32 v60, v60, v195, v194
	ds_bpermute_b32 v62, v122, v60
	s_lshl_b32 s12, s37, 6
	s_add_i32 s13, s12, 0x7fffc000
	s_and_b32 s13, s13, 0x7ffff800
	s_and_b32 s50, s56, s86
	s_waitcnt lgkmcnt(0)
	v_max_f32_e32 v62, v62, v62
	v_max_f32_e32 v60, v60, v62
	ds_bpermute_b32 v62, v123, v60
	s_add_i32 s37, s13, 0x4000
	s_and_b32 s51, s12, 0x2000
	s_and_b64 s[12:13], s[40:41], exec
	s_cselect_b32 s13, 7, 5
	s_waitcnt lgkmcnt(0)
	v_max_f32_e32 v62, v62, v62
	v_max_f32_e32 v60, v60, v62
	v_sub_f32_e32 v63, v65, v60
	v_mul_f32_e32 v63, 0x3fb8aa3b, v63
	v_exp_f32_e32 v107, v63
	v_sub_f32_e32 v63, v96, v60
	v_mul_f32_e32 v63, 0x3fb8aa3b, v63
	v_exp_f32_e32 v96, v63
	v_sub_f32_e32 v63, v67, v60
	v_mul_f32_e32 v63, 0x3fb8aa3b, v63
	v_exp_f32_e32 v150, v63
	v_sub_f32_e32 v63, v98, v60
	v_mul_f32_e32 v63, 0x3fb8aa3b, v63
	v_exp_f32_e32 v98, v63
	v_sub_f32_e32 v63, v97, v60
	v_mul_f32_e32 v63, 0x3fb8aa3b, v63
	v_exp_f32_e32 v97, v63
	v_sub_f32_e32 v63, v93, v60
	v_mul_f32_e32 v63, 0x3fb8aa3b, v63
	v_exp_f32_e32 v151, v63
	v_sub_f32_e32 v63, v92, v60
	v_mul_f32_e32 v63, 0x3fb8aa3b, v63
	v_exp_f32_e32 v152, v63
	v_sub_f32_e32 v63, v95, v60
	v_mul_f32_e32 v63, 0x3fb8aa3b, v63
	v_exp_f32_e32 v92, v63
	v_sub_f32_e32 v63, v94, v60
	v_mul_f32_e32 v63, 0x3fb8aa3b, v63
	v_exp_f32_e32 v93, v63
	v_sub_f32_e32 v63, v89, v60
	v_sub_f32_e32 v62, v66, v60
	v_mul_f32_e32 v63, 0x3fb8aa3b, v63
	v_mul_f32_e32 v62, 0x3fb8aa3b, v62
	v_exp_f32_e32 v89, v63
	v_sub_f32_e32 v63, v88, v60
	v_exp_f32_e32 v105, v62
	v_mul_f32_e32 v63, 0x3fb8aa3b, v63
	v_exp_f32_e32 v88, v63
	v_sub_f32_e32 v63, v91, v60
	v_mul_f32_e32 v63, 0x3fb8aa3b, v63
	v_exp_f32_e32 v91, v63
	v_sub_f32_e32 v63, v90, v60
	v_add_f32_e32 v62, 0, v105
	v_mul_f32_e32 v63, 0x3fb8aa3b, v63
	v_add_f32_e32 v62, v107, v62
	v_exp_f32_e32 v90, v63
	v_sub_f32_e32 v63, v85, v60
	v_add_f32_e32 v62, v96, v62
	v_mul_f32_e32 v63, 0x3fb8aa3b, v63
	v_add_f32_e32 v62, v150, v62
	v_exp_f32_e32 v85, v63
	v_sub_f32_e32 v63, v84, v60
	v_add_f32_e32 v62, v98, v62
	v_mul_f32_e32 v63, 0x3fb8aa3b, v63
	v_add_f32_e32 v62, v97, v62
	v_exp_f32_e32 v196, v63
	v_sub_f32_e32 v63, v87, v60
	v_add_f32_e32 v62, v151, v62
	v_mul_f32_e32 v63, 0x3fb8aa3b, v63
	v_add_f32_e32 v62, v152, v62
	v_exp_f32_e32 v77, v63
	v_sub_f32_e32 v63, v86, v60
	v_add_f32_e32 v62, v92, v62
	v_mul_f32_e32 v63, 0x3fb8aa3b, v63
	v_bfe_u32 v87, v97, 16, 1
	v_bfe_u32 v95, v107, 16, 1
	v_add_f32_e32 v62, v93, v62
	v_exp_f32_e32 v79, v63
	v_sub_f32_e32 v63, v99, v60
	v_add3_u32 v99, v107, v95, s33
	v_add3_u32 v87, v97, v87, s33
	v_bfe_u32 v95, v105, 16, 1
	v_bfe_u32 v97, v96, 16, 1
	v_bfe_u32 v107, v98, 16, 1
	v_add_f32_e32 v62, v89, v62
	v_bfe_u32 v94, v150, 16, 1
	v_add3_u32 v98, v98, v107, s33
	v_add3_u32 v96, v96, v97, s33
	v_add3_u32 v95, v105, v95, s33
	v_add_f32_e32 v62, v88, v62
	v_add3_u32 v94, v150, v94, s33
	v_bfe_u32 v150, v151, 16, 1
	v_lshrrev_b32_e32 v105, 16, v95
	v_lshrrev_b32_e32 v95, 16, v96
	v_lshrrev_b32_e32 v96, 16, v98
	v_add_f32_e32 v62, v91, v62
	v_bfe_u32 v86, v152, 16, 1
	v_add3_u32 v150, v151, v150, s33
	v_and_or_b32 v96, v87, s11, v96
	v_and_or_b32 v95, v94, s11, v95
	v_and_or_b32 v94, v99, s11, v105
	v_bfe_u32 v87, v90, 16, 1
	v_bfe_u32 v98, v88, 16, 1
	v_bfe_u32 v99, v93, 16, 1
	v_add_f32_e32 v62, v90, v62
	v_add3_u32 v86, v152, v86, s33
	v_lshrrev_b32_e32 v97, 16, v150
	ds_read_b64_tr_b16 v[152:153], v186 offset:30208
	ds_read_b64_tr_b16 v[150:151], v186 offset:27648
	ds_read_b64_tr_b16 v[198:199], v186 offset:27680
	ds_read_b64_tr_b16 v[200:201], v186 offset:30240
	v_add3_u32 v93, v93, v99, s33
	v_add3_u32 v98, v88, v98, s33
	v_add3_u32 v87, v90, v87, s33
	v_bfe_u32 v88, v92, 16, 1
	v_bfe_u32 v90, v89, 16, 1
	v_bfe_u32 v99, v91, 16, 1
	v_bfe_u32 v105, v85, 16, 1
	v_add_f32_e32 v62, v85, v62
	v_and_or_b32 v97, v86, s11, v97
	v_add3_u32 v91, v91, v99, s33
	v_add3_u32 v89, v89, v90, s33
	v_add3_u32 v88, v92, v88, s33
	v_lshrrev_b32_e32 v90, 16, v88
	v_lshrrev_b32_e32 v92, 16, v89
	v_lshrrev_b32_e32 v88, 16, v91
	ds_read_b64_tr_b16 v[202:203], v186 offset:27712
	ds_read_b64_tr_b16 v[204:205], v186 offset:30272
	ds_read_b64_tr_b16 v[206:207], v186 offset:27744
	ds_read_b64_tr_b16 v[208:209], v186 offset:30304
	v_cvt_pk_bf16_f32 v89, v85, v196
	v_and_or_b32 v88, v87, s11, v88
	v_and_or_b32 v87, v98, s11, v92
	v_and_or_b32 v86, v93, s11, v90
	ds_read_b64_tr_b16 v[90:91], v186 offset:32768
	ds_read_b64_tr_b16 v[92:93], v186 offset:35328
	ds_read_b64_tr_b16 v[236:237], v186 offset:32800
	ds_read_b64_tr_b16 v[238:239], v186 offset:35360
	ds_read_b64_tr_b16 v[246:247], v186 offset:32832
	ds_read_b64_tr_b16 v[248:249], v186 offset:35392
	ds_read_b64_tr_b16 v[210:211], v186 offset:32864
	ds_read_b64_tr_b16 v[212:213], v186 offset:35424
	s_waitcnt lgkmcnt(14)
	v_mfma_f32_16x16x32_bf16 v[150:153], v[150:153], v[94:97], 0
	v_mul_f32_e32 v63, 0x3fb8aa3b, v63
	v_exp_f32_e32 v78, v63
	v_sub_f32_e32 v63, v80, v60
	s_waitcnt lgkmcnt(6)
; #define LAS __attribute__((address_space(3)))
; __device__ __forceinline__ unsigned pk2(float lo, float hi) { return f2bf(lo) | (f2bf(hi) << 16); }
; #define MFMA16(a, b, c) __builtin_amdgcn_mfma_f32_16x16x32_bf16(a, b, c, 0, 0, 0)
; __device__ __forceinline__ v4i16_t vtr(const LAS unsigned char* p) { return __builtin_amdgcn_ds_read_tr16_b64_v4i16((LAS v4i16_t*)p); }
; __device__ __forceinline__ void attn_phase(const Params& p, LAS unsigned char* lds, const int bx, const int G, const int tid) {
;     ...
;             for (int e = 0; e < 4; ++e) { const float pv = __expf(st[j][e] - mx); st[j][e] = pv; sm += pv; }
;         sm += __shfl_xor(sm, 16); sm += __shfl_xor(sm, 32);
;         f32x4 ot[4];
; #pragma unroll
;         for (int dt = 0; dt < 4; ++dt) ot[dt] = (f32x4){0.f, 0.f, 0.f, 0.f};
; #pragma unroll
;         for (int ks = 0; ks < 5; ++ks) { v4u pw; pw.x = pk2(st[2 * ks][0], st[2 * ks][1]); pw.y = pk2(st[2 * ks][2], st[2 * ks][3]); pw.z = pk2(st[2 * ks + 1][0], st[2 * ks + 1][1]); pw.w = pk2(st[2 * ks + 1][2], st[2 * ks + 1][3]);
;             const bf16x8 pb = __builtin_bit_cast(bf16x8, pw);
; #pragma unroll
;             for (int dt = 0; dt < 4; ++dt) { const LAS unsigned char* vr = vbp + ks * 5120 + dt * 32;
;                 const v4i16_t lo = vtr(vr), hi = vtr(vr + 16 * 160);
;                 ot[dt] = MFMA16(__builtin_shufflevector(lo, hi, 0, 1, 2, 3, 4, 5, 6, 7), pb, ot[dt]); } }
	v_mfma_f32_16x16x32_bf16 v[90:93], v[90:93], v[86:89], v[150:153]
	s_nop 2
	ds_read_b64_tr_b16 v[214:215], v186 offset:37888
	ds_read_b64_tr_b16 v[216:217], v186 offset:40448
	v_mul_f32_e32 v63, 0x3fb8aa3b, v63
	v_exp_f32_e32 v80, v63
	v_mfma_f32_16x16x32_bf16 v[198:201], v[198:201], v[94:97], 0
	v_sub_f32_e32 v63, v82, v60
	v_mul_f32_e32 v63, 0x3fb8aa3b, v63
	v_exp_f32_e32 v82, v63
	s_waitcnt lgkmcnt(6)
	v_mfma_f32_16x16x32_bf16 v[150:153], v[236:239], v[86:89], v[198:201]
	s_nop 2
	ds_read_b64_tr_b16 v[218:219], v186 offset:37920
	ds_read_b64_tr_b16 v[220:221], v186 offset:40480
	v_sub_f32_e32 v63, v81, v60
	v_mul_f32_e32 v63, 0x3fb8aa3b, v63
	v_mfma_f32_16x16x32_bf16 v[202:205], v[202:205], v[94:97], 0
	v_exp_f32_e32 v81, v63
	v_sub_f32_e32 v63, v83, v60
	v_add_f32_e32 v62, v196, v62
	v_mul_f32_e32 v63, 0x3fb8aa3b, v63
	s_waitcnt lgkmcnt(6)
	v_mfma_f32_16x16x32_bf16 v[198:201], v[246:249], v[86:89], v[202:205]
	s_nop 2
	ds_read_b64_tr_b16 v[222:223], v186 offset:37952
	ds_read_b64_tr_b16 v[224:225], v186 offset:40512
	v_add_f32_e32 v62, v77, v62
	v_exp_f32_e32 v83, v63
	v_sub_f32_e32 v63, v76, v60
	v_mfma_f32_16x16x32_bf16 v[94:97], v[206:209], v[94:97], 0
	v_add_f32_e32 v62, v79, v62
	v_mul_f32_e32 v63, 0x3fb8aa3b, v63
	v_add_f32_e32 v62, v78, v62
	v_exp_f32_e32 v84, v63
	v_add_f32_e32 v62, v80, v62
	v_add_f32_e32 v62, v82, v62
	s_waitcnt lgkmcnt(6)
	v_mfma_f32_16x16x32_bf16 v[86:89], v[210:213], v[86:89], v[94:97]
	ds_read_b64_tr_b16 v[226:227], v186 offset:37984
	ds_read_b64_tr_b16 v[228:229], v186 offset:40544
	v_add_f32_e32 v62, v81, v62
	v_sub_f32_e32 v63, v188, v60
	v_add_f32_e32 v62, v83, v62
	v_bfe_u32 v94, v81, 16, 1
	v_bfe_u32 v95, v80, 16, 1
	v_bfe_u32 v96, v79, 16, 1
	v_add3_u32 v96, v79, v96, s33
	v_add3_u32 v79, v80, v95, s33
	v_add3_u32 v80, v81, v94, s33
	v_bfe_u32 v94, v82, 16, 1
	v_bfe_u32 v95, v83, 16, 1
	v_mul_f32_e32 v63, 0x3fb8aa3b, v63
	v_bfe_u32 v85, v84, 16, 1
	v_add3_u32 v83, v83, v95, s33
	v_add3_u32 v82, v82, v94, s33
	v_add_f32_e32 v62, v84, v62
	v_exp_f32_e32 v69, v63
	v_sub_f32_e32 v63, v187, v60
	v_add3_u32 v81, v84, v85, s33
	v_bfe_u32 v84, v77, 16, 1
	v_bfe_u32 v85, v78, 16, 1
	v_lshrrev_b32_e32 v82, 16, v82
	v_lshrrev_b32_e32 v83, 16, v83
	v_mul_f32_e32 v63, 0x3fb8aa3b, v63
	v_add3_u32 v78, v78, v85, s33
	v_add3_u32 v77, v77, v84, s33
	v_and_or_b32 v81, v81, s11, v83
	v_and_or_b32 v80, v80, s11, v82
	v_exp_f32_e32 v71, v63
	v_sub_f32_e32 v63, v73, v60
	v_mul_f32_e32 v63, 0x3fb8aa3b, v63
	v_exp_f32_e32 v70, v63
	v_sub_f32_e32 v63, v72, v60
	v_lshrrev_b32_e32 v77, 16, v77
	v_lshrrev_b32_e32 v78, 16, v78
	v_mul_f32_e32 v63, 0x3fb8aa3b, v63
	v_and_or_b32 v79, v79, s11, v78
	v_and_or_b32 v78, v96, s11, v77
	v_exp_f32_e32 v73, v63
	v_sub_f32_e32 v63, v75, v60
	s_waitcnt lgkmcnt(6)
	v_mfma_f32_16x16x32_bf16 v[82:85], v[214:217], v[78:81], v[90:93]
	s_nop 2
	v_mul_f32_e32 v63, 0x3fb8aa3b, v63
	v_exp_f32_e32 v72, v63
	v_sub_f32_e32 v63, v74, v60
	v_mul_f32_e32 v63, 0x3fb8aa3b, v63
	v_exp_f32_e32 v75, v63
	v_sub_f32_e32 v63, v190, v60
	v_mul_f32_e32 v63, 0x3fb8aa3b, v63
	s_waitcnt lgkmcnt(4)
	v_mfma_f32_16x16x32_bf16 v[90:93], v[218:221], v[78:81], v[150:153]
	s_nop 0
	v_add_f32_e32 v62, v69, v62
	v_exp_f32_e32 v74, v63
	v_sub_f32_e32 v63, v68, v60
	v_add_f32_e32 v62, v71, v62
	v_mul_f32_e32 v63, 0x3fb8aa3b, v63
	v_add_f32_e32 v62, v70, v62
	v_exp_f32_e32 v76, v63
	v_add_f32_e32 v62, v73, v62
	v_add_f32_e32 v62, v72, v62
	s_waitcnt lgkmcnt(2)
	v_mfma_f32_16x16x32_bf16 v[94:97], v[222:225], v[78:81], v[198:201]
	v_add_f32_e32 v62, v75, v62
	v_add_f32_e32 v62, v74, v62
	v_bfe_u32 v77, v76, 16, 1
	s_waitcnt lgkmcnt(0)
	v_mfma_f32_16x16x32_bf16 v[78:81], v[226:229], v[78:81], v[86:89]
	v_add_f32_e32 v62, v76, v62
	v_sub_f32_e32 v63, v192, v60
	v_mul_f32_e32 v63, 0x3fb8aa3b, v63
	v_bfe_u32 v86, v75, 16, 1
	v_bfe_u32 v87, v73, 16, 1
	v_bfe_u32 v88, v71, 16, 1
	v_add3_u32 v88, v71, v88, s33
	v_add3_u32 v71, v73, v87, s33
	v_bfe_u32 v87, v74, 16, 1
	v_add3_u32 v74, v74, v87, s33
	v_add3_u32 v73, v76, v77, s33
	v_bfe_u32 v76, v69, 16, 1
	v_bfe_u32 v77, v70, 16, 1
	v_lshrrev_b32_e32 v74, 16, v74
	v_add3_u32 v70, v70, v77, s33
	v_add3_u32 v69, v69, v76, s33
	v_and_or_b32 v73, v73, s11, v74
	v_cvt_pk_bf16_f32 v72, v72, v75
	ds_read_b64_tr_b16 v[74:75], v186 offset:43008
	ds_read_b64_tr_b16 v[76:77], v186 offset:45568
	v_lshrrev_b32_e32 v69, 16, v69
	v_lshrrev_b32_e32 v70, 16, v70
	v_and_or_b32 v71, v71, s11, v70
	v_and_or_b32 v70, v88, s11, v69
	v_exp_f32_e32 v66, v63
	v_sub_f32_e32 v63, v191, v60
	s_waitcnt lgkmcnt(0)
	v_mfma_f32_16x16x32_bf16 v[74:77], v[74:77], v[70:73], v[82:85]
	s_nop 2
	ds_read_b64_tr_b16 v[82:83], v186 offset:43040
	ds_read_b64_tr_b16 v[84:85], v186 offset:45600
	v_mul_f32_e32 v63, 0x3fb8aa3b, v63
	v_exp_f32_e32 v65, v63
	v_sub_f32_e32 v63, v195, v60
	v_mul_f32_e32 v63, 0x3fb8aa3b, v63
	v_exp_f32_e32 v67, v63
	v_sub_f32_e32 v63, v194, v60
	s_waitcnt lgkmcnt(0)
; #define LAS __attribute__((address_space(3)))
; __device__ __forceinline__ unsigned pk2(float lo, float hi) { return f2bf(lo) | (f2bf(hi) << 16); }
; #define MFMA16(a, b, c) __builtin_amdgcn_mfma_f32_16x16x32_bf16(a, b, c, 0, 0, 0)
; __device__ __forceinline__ v4i16_t vtr(const LAS unsigned char* p) { return __builtin_amdgcn_ds_read_tr16_b64_v4i16((LAS v4i16_t*)p); }
; __device__ __forceinline__ void attn_phase(const Params& p, LAS unsigned char* lds, const int bx, const int G, const int tid) {
;     ...
;         for (int ks = 0; ks < 5; ++ks) { v4u pw; pw.x = pk2(st[2 * ks][0], st[2 * ks][1]); pw.y = pk2(st[2 * ks][2], st[2 * ks][3]); pw.z = pk2(st[2 * ks + 1][0], st[2 * ks + 1][1]); pw.w = pk2(st[2 * ks + 1][2], st[2 * ks + 1][3]);
;             const bf16x8 pb = __builtin_bit_cast(bf16x8, pw);
; #pragma unroll
;             for (int dt = 0; dt < 4; ++dt) { const LAS unsigned char* vr = vbp + ks * 5120 + dt * 32;
;                 const v4i16_t lo = vtr(vr), hi = vtr(vr + 16 * 160);
;                 ot[dt] = MFMA16(__builtin_shufflevector(lo, hi, 0, 1, 2, 3, 4, 5, 6, 7), pb, ot[dt]); } }
;         { const size_t m = (size_t)(X.m0 + (X.nb * 64 + qi) * d + X.r); const float inv = 1.f / sm;
; #pragma unroll
;           for (int dt = 0; dt < 4; ++dt) { unsigned long long w = (unsigned long long)pk2(ot[dt][0] * inv, ot[dt][1] * inv) | ((unsigned long long)pk2(ot[dt][2] * inv, ot[dt][3] * inv) << 32);
	v_mfma_f32_16x16x32_bf16 v[82:85], v[82:85], v[70:73], v[90:93]
	ds_read_b64_tr_b16 v[86:87], v186 offset:43072
	ds_read_b64_tr_b16 v[88:89], v186 offset:45632
	s_nop 0
	ds_read_b64_tr_b16 v[90:91], v186 offset:43104
	ds_read_b64_tr_b16 v[92:93], v186 offset:45664
	v_mul_f32_e32 v63, 0x3fb8aa3b, v63
	v_exp_f32_e32 v68, v63
	v_add_f32_e32 v62, v66, v62
	v_add_f32_e32 v62, v65, v62
	v_add_f32_e32 v62, v67, v62
	s_waitcnt lgkmcnt(2)
	v_mfma_f32_16x16x32_bf16 v[86:89], v[86:89], v[70:73], v[94:97]
	v_add_f32_e32 v62, v68, v62
	ds_bpermute_b32 v63, v122, v62
	v_and_b32_sdwa v69, v67, v189 dst_sel:DWORD dst_unused:UNUSED_PAD src0_sel:WORD_1 src1_sel:DWORD
	s_waitcnt lgkmcnt(1)
	v_mfma_f32_16x16x32_bf16 v[70:73], v[90:93], v[70:73], v[78:81]
	v_add3_u32 v67, v67, v69, s33
	v_and_b32_sdwa v69, v68, v189 dst_sel:DWORD dst_unused:UNUSED_PAD src0_sel:WORD_1 src1_sel:DWORD
	v_add3_u32 v68, v68, v69, s33
	v_and_b32_sdwa v78, v66, v189 dst_sel:DWORD dst_unused:UNUSED_PAD src0_sel:WORD_1 src1_sel:DWORD
	v_add3_u32 v66, v66, v78, s33
	v_and_b32_sdwa v78, v65, v189 dst_sel:DWORD dst_unused:UNUSED_PAD src0_sel:WORD_1 src1_sel:DWORD
	v_add3_u32 v65, v65, v78, s33
	ds_read_b64_tr_b16 v[78:79], v186 offset:48128
	ds_read_b64_tr_b16 v[80:81], v186 offset:50688
	v_and_b32_e32 v68, 0xffff0000, v68
	v_and_b32_e32 v65, 0xffff0000, v65
	v_or_b32_sdwa v67, v68, v67 dst_sel:DWORD dst_unused:UNUSED_PAD src0_sel:DWORD src1_sel:WORD_1
	v_or_b32_sdwa v66, v65, v66 dst_sel:DWORD dst_unused:UNUSED_PAD src0_sel:DWORD src1_sel:WORD_1
	v_mov_b32_e32 v68, v0
	v_mov_b32_e32 v69, v0
	s_waitcnt lgkmcnt(2)
	v_add_f32_e32 v62, v62, v63
	ds_bpermute_b32 v63, v123, v62
	s_waitcnt lgkmcnt(1)
	v_mfma_f32_16x16x32_bf16 v[74:77], v[78:81], v[66:69], v[74:77]
	ds_read_b64_tr_b16 v[78:79], v186 offset:48160
	ds_read_b64_tr_b16 v[80:81], v186 offset:50720
	v_sub_u32_e32 v61, s13, v3
	s_cselect_b32 s12, s51, s37
	v_lshrrev_b32_e64 v61, v61, s50
	s_waitcnt lgkmcnt(0)
	v_mfma_f32_16x16x32_bf16 v[78:81], v[78:81], v[66:69], v[82:85]
	s_nop 2
	ds_read_b64_tr_b16 v[82:83], v186 offset:48192
	ds_read_b64_tr_b16 v[84:85], v186 offset:50752
	v_add_f32_e32 v62, v62, v63
	v_or_b32_e32 v63, v64, v121
	v_or_b32_e32 v61, s12, v61
	v_lshl_add_u32 v61, v63, v3, v61
	v_div_scale_f32 v3, s[12:13], v62, v62, 1.0
	v_rcp_f32_e32 v63, v3
	s_waitcnt lgkmcnt(0)
	v_mfma_f32_16x16x32_bf16 v[82:85], v[82:85], v[66:69], v[86:89]
	s_nop 2
	ds_read_b64_tr_b16 v[86:87], v186 offset:48224
	ds_read_b64_tr_b16 v[88:89], v186 offset:50784
	v_mov_b32_e32 v107, v0
	v_fma_f32 v64, -v3, v63, 1.0
	v_fmac_f32_e32 v63, v64, v63
	v_div_scale_f32 v64, vcc, 1.0, v62, 1.0
	v_mul_f32_e32 v65, v64, v63
	s_waitcnt lgkmcnt(0)
	v_mfma_f32_16x16x32_bf16 v[66:69], v[86:89], v[66:69], v[70:73]
	v_readlane_b32 s2, v254, 55
	v_readlane_b32 s3, v254, 56
	s_nop 0
	v_fma_f32 v70, -v3, v65, v64
	v_fmac_f32_e32 v65, v70, v63
	v_fma_f32 v3, -v3, v65, v64
	v_div_fmas_f32 v3, v3, v63, v65
	v_div_fixup_f32 v3, v3, v62, 1.0
	v_mov_b64_e32 v[64:65], s[90:91]
	v_lshlrev_b32_e32 v70, 6, v2
	v_mad_i64_i32 v[64:65], s[12:13], v61, s57, v[64:65]
	v_ashrrev_i32_e32 v71, 31, v70
	v_mul_f32_e32 v63, v3, v74
	v_lshl_add_u64 v[64:65], v[70:71], 1, v[64:65]
	v_mul_f32_e32 v70, v3, v75
	v_bfe_u32 v71, v63, 16, 1
	v_cvt_pk_bf16_f32 v70, v63, v70
	v_mul_f32_e32 v63, v3, v76
	v_mul_f32_e32 v71, v3, v77
	v_lshl_add_u64 v[64:65], v[64:65], 0, v[106:107]
	v_cvt_pk_bf16_f32 v71, v63, v71
	v_mul_f32_e32 v63, v3, v78
	global_store_dwordx2 v[64:65], v[70:71], off
	v_mul_f32_e32 v70, v3, v79
	v_cvt_pk_bf16_f32 v70, v63, v70
	v_mul_f32_e32 v63, v3, v80
	v_mul_f32_e32 v71, v3, v81
	v_cvt_pk_bf16_f32 v71, v63, v71
	v_mul_f32_e32 v63, v3, v82
	global_store_dwordx2 v[64:65], v[70:71], off offset:32
	v_mul_f32_e32 v70, v3, v83
	v_cvt_pk_bf16_f32 v70, v63, v70
	v_mul_f32_e32 v63, v3, v84
	v_mul_f32_e32 v71, v3, v85
	v_bfe_u32 v72, v71, 16, 1
	v_cvt_pk_bf16_f32 v71, v63, v71
	v_mul_f32_e32 v63, v3, v66
	v_mul_f32_e32 v66, v3, v67
	v_cvt_pk_bf16_f32 v66, v63, v66
	v_mul_f32_e32 v63, v3, v68
	v_mul_f32_e32 v3, v3, v69
	v_bfe_u32 v67, v63, 16, 1
	v_add3_u32 v63, v63, v67, s33
	v_bfe_u32 v67, v3, 16, 1
	v_lshrrev_b32_e32 v63, 16, v63
	v_add3_u32 v3, v3, v67, s33
	v_and_or_b32 v67, v3, s11, v63
	global_store_dwordx2 v[64:65], v[70:71], off offset:64
	global_store_dwordx2 v[64:65], v[66:67], off offset:96
	s_and_saveexec_b64 s[12:13], s[2:3]
	s_cbranch_execz .LBB0_386
	s_mov_b32 s37, 0x800000
	v_cmp_gt_f32_e32 vcc, s37, v62
	s_mov_b32 s37, 0x3f317217
	s_mov_b32 s2, 0x7f800000
	v_cndmask_b32_e64 v3, 0, 32, vcc
	v_ldexp_f32 v3, v62, v3
	v_log_f32_e32 v3, v3
	v_cndmask_b32_e32 v62, 0, v233, vcc
	v_mul_f32_e32 v63, 0x3f317217, v3
	v_fma_f32 v63, v3, s37, -v63
	v_fmac_f32_e32 v63, 0x3377d1cf, v3
	v_fmac_f32_e32 v63, 0x3f317217, v3
	v_cmp_lt_f32_e64 vcc, |v3|, s2
	v_readlane_b32 s2, v253, 7
	v_readlane_b32 s3, v253, 8
	v_cndmask_b32_e32 v3, v3, v63, vcc
	v_sub_f32_e32 v3, v3, v62
	v_add_f32_e32 v62, v60, v3
	v_ashrrev_i32_e32 v3, 31, v2
	v_mad_i64_i32 v[60:61], s[40:41], v61, 48, s[2:3]
	v_lshl_add_u64 v[2:3], v[2:3], 2, v[60:61]
	global_store_dword v[2:3], v62, off
	s_branch .LBB0_386
